# P1/P12 idle-tail conversion items claimed dynamically from a global counter (every workgroup joins when its GEMM units are done)
# baseline (speedup 1.0000x reference)
.LBB0_229:
	s_abs_i32 s0, s33
	v_cvt_f32_u32_e32 v0, s0
	s_sub_i32 s1, 0, s0
	v_rcp_iflag_f32_e32 v0, v0
	s_nop 0
	v_mul_f32_e32 v0, 0x4f7ffffe, v0
	v_cvt_u32_f32_e32 v0, v0
	s_nop 0
	v_readfirstlane_b32 s2, v0
	s_mul_i32 s1, s1, s2
	s_mul_hi_u32 s1, s2, s1
	s_add_i32 s2, s2, s1
	s_mul_hi_u32 s1, s2, 0xb6c
	s_mul_i32 s1, s1, s0
	s_sub_i32 s1, 0xb6c, s1
	s_sub_i32 s2, s1, s0
	s_cmp_ge_u32 s1, s0
	s_cselect_b32 s1, s2, s1
	s_sub_i32 s2, s1, s0
	s_cmp_ge_u32 s1, s0
	s_cselect_b32 s0, s2, s1
	s_sub_i32 s1, s95, s0
	s_cmp_lt_i32 s1, 0
	s_nop 0
	s_lshl_b32 s1, s1, 3
	v_readlane_b32 s2, v254, 16
	s_add_i32 s3, s1, s2
	s_cmpk_gt_i32 s3, 0x157f
	s_nop 0
	v_lshlrev_b32_e32 v1, 2, v135
	v_ashrrev_i32_e32 v133, 3, v135
	v_ashrrev_i32_e32 v0, 4, v135
	v_lshlrev_b32_e32 v3, 4, v135
	v_bitop3_b32 v12, v133, 28, v1 bitop3:0x48
	v_add_u32_e32 v135, 8, v133
	v_readlane_b32 s5, v254, 17
	v_lshlrev_b32_e32 v11, 7, v133
	v_lshlrev_b32_e32 v12, 2, v12
	v_bitop3_b32 v13, v135, 28, v1 bitop3:0x48
	v_add3_u32 v134, s5, v11, v12
	v_lshlrev_b32_e32 v11, 7, v135
	v_lshlrev_b32_e32 v13, 2, v13
	v_add_u32_e32 v137, 16, v133
	v_add3_u32 v136, s5, v11, v13
	v_bitop3_b32 v13, v137, 28, v1 bitop3:0x48
	v_lshlrev_b32_e32 v11, 7, v137
	v_lshlrev_b32_e32 v13, 2, v13
	v_add_u32_e32 v139, 24, v133
	v_add3_u32 v138, s5, v11, v13
	v_bitop3_b32 v13, v139, 28, v1 bitop3:0x48
	v_lshlrev_b32_e32 v11, 7, v139
	v_lshlrev_b32_e32 v13, 2, v13
	v_add_u32_e32 v141, 32, v133
	v_add3_u32 v140, s5, v11, v13
	v_lshlrev_b32_e32 v11, 7, v141
	v_add_u32_e32 v143, 40, v133
	v_add3_u32 v142, s5, v11, v12
	v_bitop3_b32 v12, v143, 28, v1 bitop3:0x48
	v_lshlrev_b32_e32 v132, 2, v0
	v_lshlrev_b32_e32 v11, 7, v143
	v_lshlrev_b32_e32 v12, 2, v12
	v_add_u32_e32 v145, 48, v133
	v_add_u32_e32 v2, s5, v132
	v_and_b32_e32 v128, 0x70, v3
	s_movk_i32 s4, 0x50
	v_readlane_b32 s6, v254, 29
	v_add3_u32 v144, s5, v11, v12
	v_bitop3_b32 v12, v145, 28, v1 bitop3:0x48
	v_add_u32_e32 v147, 56, v133
	s_sub_i32 s1, s33, s0
	v_and_b32_e32 v0, 60, v1
	v_mov_b32_e32 v129, 0
	s_movk_i32 s2, 0x70
	v_xad_u32 v9, v128, s4, v2
	s_movk_i32 s4, 0x60
	v_readlane_b32 s7, v254, 30
	v_lshlrev_b32_e32 v11, 7, v145
	v_lshlrev_b32_e32 v12, 2, v12
	v_bitop3_b32 v1, v147, 28, v1 bitop3:0x48
	v_add_u32_e32 v3, v2, v128
	v_lshlrev_b32_e32 v4, 7, v0
	v_xad_u32 v5, v128, 16, v2
	v_xad_u32 v6, v128, 32, v2
	v_xad_u32 v7, v128, 48, v2
	v_xad_u32 v8, v128, 64, v2
	v_xad_u32 v10, v128, s4, v2
	v_xad_u32 v2, v128, s2, v2
	v_lshl_add_u64 v[130:131], s[6:7], 0, v[128:129]
	v_add3_u32 v146, s5, v11, v12
	v_lshlrev_b32_e32 v11, 7, v147
	v_lshlrev_b32_e32 v1, 2, v1
	s_lshl_b32 s6, s1, 3
	s_lshl_b32 s1, s33, 4
	s_lshl_b32 s2, s0, 4
	s_lshl_b32 s0, s0, 9
	v_readlane_b32 s52, v255, 7
	v_add3_u32 v148, s5, v11, v1
	s_lshl_b32 s7, s3, 1
	s_sub_i32 s10, s1, s2
	s_lshl_b32 s11, s3, 6
	s_sub_i32 s12, s44, s0
	s_mov_b32 s1, 0
	v_lshlrev_b32_e32 v128, 2, v0
	s_mov_b32 s13, 0xc3e00000
	v_mov_b32_e32 v149, 0x43e00000
	v_add_u32_e32 v150, v3, v4
	v_add_u32_e32 v151, v5, v4
	v_add_u32_e32 v152, v6, v4
	v_add_u32_e32 v153, v7, v4
	v_add_u32_e32 v154, v8, v4
	v_add_u32_e32 v155, v9, v4
	v_add_u32_e32 v156, v10, v4
	v_add_u32_e32 v157, v2, v4
	s_movk_i32 s14, 0x2b00
	v_readlane_b32 s66, v255, 21
	v_readlane_b32 s67, v255, 22
	v_readlane_b32 s53, v255, 8
	v_readlane_b32 s54, v255, 9
	v_readlane_b32 s55, v255, 10
	v_readlane_b32 s56, v255, 11
	v_readlane_b32 s57, v255, 12
	v_readlane_b32 s58, v255, 13
	v_readlane_b32 s59, v255, 14
	v_readlane_b32 s60, v255, 15
	v_readlane_b32 s61, v255, 16
	v_readlane_b32 s62, v255, 17
	v_readlane_b32 s63, v255, 18
	v_readlane_b32 s64, v255, 19
	v_readlane_b32 s65, v255, 20
	s_add_u32 s16, s34, 0x8000
	s_addc_u32 s17, s35, 0
	v_mov_b32_e32 v251, 1
	v_mov_b32_e32 v252, 0
	s_movk_i32 s23, 0x60
	s_mov_b64 s[20:21], exec
	s_mov_b64 exec, 1
	global_atomic_add v250, v252, v251, s[16:17] sc0
	s_mov_b64 exec, s[20:21]
	s_waitcnt vmcnt(0)
	v_readfirstlane_b32 s3, v250
	s_nop 3
	s_cmpk_gt_i32 s3, 0x157f
	s_cbranch_scc1 .LBB0_233
	s_lshl_b32 s7, s3, 1
	s_lshl_b32 s11, s3, 6
.LBB0_232:
	s_and_b32 s4, s7, 0xffffff80
	v_add_u32_e32 v0, s4, v132
	v_ashrrev_i32_e32 v1, 31, v0
	s_and_b32 s2, s11, 0xfc0
	v_lshlrev_b64 v[0:1], 14, v[0:1]
	v_lshl_add_u64 v[0:1], s[66:67], 0, v[0:1]
	s_lshl_b32 s0, s2, 2
	v_lshl_add_u64 v[0:1], v[0:1], 0, s[0:1]
	v_lshl_add_u64 v[4:5], v[0:1], 0, v[128:129]
	v_add_co_u32_e32 v0, vcc, 0x4000, v4
	global_load_dwordx4 v[120:123], v[4:5], off nt
	s_nop 0
	v_addc_co_u32_e32 v1, vcc, 0, v5, vcc
	global_load_dwordx4 v[124:127], v[0:1], off nt
	v_add_co_u32_e32 v0, vcc, 0x8000, v4
	s_nop 1
	s_nop 0
	v_addc_co_u32_e32 v1, vcc, 0, v5, vcc
	global_load_dwordx4 v[112:115], v[0:1], off nt
	v_add_co_u32_e32 v0, vcc, 0xc000, v4
	s_nop 1
	s_ashr_i32 s5, s4, 31
	s_nop 0
	v_addc_co_u32_e32 v1, vcc, 0, v5, vcc
	global_load_dwordx4 v[116:119], v[0:1], off nt
	v_add_co_u32_e32 v0, vcc, 0x40000, v4
	s_nop 1
	s_nop 0
	v_addc_co_u32_e32 v1, vcc, 0, v5, vcc
	global_load_dwordx4 v[104:107], v[0:1], off nt
	v_add_co_u32_e32 v0, vcc, 0x44000, v4
	s_nop 1
	s_nop 0
	v_addc_co_u32_e32 v1, vcc, 0, v5, vcc
	global_load_dwordx4 v[108:111], v[0:1], off nt
	v_add_co_u32_e32 v0, vcc, 0x48000, v4
	s_nop 1
	s_nop 0
	v_addc_co_u32_e32 v1, vcc, 0, v5, vcc
	global_load_dwordx4 v[96:99], v[0:1], off nt
	v_add_co_u32_e32 v0, vcc, 0x4c000, v4
	s_nop 1
	s_nop 0
	v_addc_co_u32_e32 v1, vcc, 0, v5, vcc
	global_load_dwordx4 v[100:103], v[0:1], off nt
	v_add_co_u32_e32 v0, vcc, 0x80000, v4
	s_nop 1
	v_addc_co_u32_e32 v1, vcc, 0, v5, vcc
	global_load_dwordx4 v[88:91], v[0:1], off nt
	v_add_co_u32_e32 v0, vcc, 0x84000, v4
	s_nop 1
	v_addc_co_u32_e32 v1, vcc, 0, v5, vcc
	global_load_dwordx4 v[92:95], v[0:1], off nt
	v_add_co_u32_e32 v0, vcc, 0x88000, v4
	s_nop 1
	s_nop 0
	v_addc_co_u32_e32 v1, vcc, 0, v5, vcc
	global_load_dwordx4 v[80:83], v[0:1], off nt
	v_add_co_u32_e32 v0, vcc, 0x8c000, v4
	s_nop 1
	s_nop 0
	v_addc_co_u32_e32 v1, vcc, 0, v5, vcc
	global_load_dwordx4 v[84:87], v[0:1], off nt
	v_add_co_u32_e32 v0, vcc, 0xc0000, v4
	s_nop 1
	s_nop 0
	v_addc_co_u32_e32 v1, vcc, 0, v5, vcc
	global_load_dwordx4 v[72:75], v[0:1], off nt
	v_add_co_u32_e32 v0, vcc, 0xc4000, v4
	s_nop 1
	v_addc_co_u32_e32 v1, vcc, 0, v5, vcc
	global_load_dwordx4 v[76:79], v[0:1], off nt
	v_add_co_u32_e32 v0, vcc, 0xc8000, v4
	s_nop 1
	v_addc_co_u32_e32 v1, vcc, 0, v5, vcc
	global_load_dwordx4 v[64:67], v[0:1], off nt
	v_add_co_u32_e32 v0, vcc, 0xcc000, v4
	s_nop 1
	s_nop 0
	v_addc_co_u32_e32 v1, vcc, 0, v5, vcc
	global_load_dwordx4 v[68:71], v[0:1], off nt
	v_add_co_u32_e32 v0, vcc, 0x100000, v4
	s_nop 1
	s_nop 0
	v_addc_co_u32_e32 v1, vcc, 0, v5, vcc
	global_load_dwordx4 v[56:59], v[0:1], off nt
	v_add_co_u32_e32 v0, vcc, 0x104000, v4
	s_nop 1
	v_addc_co_u32_e32 v1, vcc, 0, v5, vcc
	global_load_dwordx4 v[60:63], v[0:1], off nt
	v_add_co_u32_e32 v0, vcc, 0x108000, v4
	s_nop 1
	v_addc_co_u32_e32 v1, vcc, 0, v5, vcc
	global_load_dwordx4 v[48:51], v[0:1], off nt
	v_add_co_u32_e32 v0, vcc, 0x10c000, v4
	s_nop 1
	s_nop 0
	v_addc_co_u32_e32 v1, vcc, 0, v5, vcc
	global_load_dwordx4 v[52:55], v[0:1], off nt
	v_add_co_u32_e32 v0, vcc, 0x140000, v4
	s_nop 1
	s_nop 0
	v_addc_co_u32_e32 v1, vcc, 0, v5, vcc
	global_load_dwordx4 v[40:43], v[0:1], off nt
	v_add_co_u32_e32 v0, vcc, 0x144000, v4
	s_nop 1
	v_addc_co_u32_e32 v1, vcc, 0, v5, vcc
	global_load_dwordx4 v[44:47], v[0:1], off nt
	v_add_co_u32_e32 v0, vcc, 0x148000, v4
	s_nop 1
	v_addc_co_u32_e32 v1, vcc, 0, v5, vcc
	global_load_dwordx4 v[32:35], v[0:1], off nt
	v_add_co_u32_e32 v0, vcc, 0x14c000, v4
	s_nop 1
	s_nop 0
	v_addc_co_u32_e32 v1, vcc, 0, v5, vcc
	global_load_dwordx4 v[36:39], v[0:1], off nt
	v_add_co_u32_e32 v0, vcc, 0x180000, v4
	s_nop 1
	s_nop 0
	v_addc_co_u32_e32 v1, vcc, 0, v5, vcc
	global_load_dwordx4 v[24:27], v[0:1], off nt
	v_add_co_u32_e32 v0, vcc, 0x184000, v4
	s_nop 1
	v_addc_co_u32_e32 v1, vcc, 0, v5, vcc
	global_load_dwordx4 v[28:31], v[0:1], off nt
	v_add_co_u32_e32 v0, vcc, 0x188000, v4
	s_nop 1
	v_addc_co_u32_e32 v1, vcc, 0, v5, vcc
	global_load_dwordx4 v[16:19], v[0:1], off nt
	v_add_co_u32_e32 v0, vcc, 0x18c000, v4
	s_nop 1
	s_nop 0
	v_addc_co_u32_e32 v1, vcc, 0, v5, vcc
	global_load_dwordx4 v[20:23], v[0:1], off nt
	v_add_co_u32_e32 v0, vcc, 0x1c0000, v4
	s_nop 1
	s_nop 0
	v_addc_co_u32_e32 v1, vcc, 0, v5, vcc
	global_load_dwordx4 v[8:11], v[0:1], off nt
	v_add_co_u32_e32 v0, vcc, 0x1c4000, v4
	s_nop 1
	v_addc_co_u32_e32 v1, vcc, 0, v5, vcc
	global_load_dwordx4 v[12:15], v[0:1], off nt
	v_add_co_u32_e32 v0, vcc, 0x1c8000, v4
	s_nop 1
	v_addc_co_u32_e32 v1, vcc, 0, v5, vcc
	v_add_co_u32_e32 v4, vcc, 0x1cc000, v4
	s_nop 1
	s_nop 0
	v_addc_co_u32_e32 v5, vcc, 0, v5, vcc
	global_load_dwordx4 v[0:3], v[0:1], off nt
	global_load_dwordx4 v[4:7], v[4:5], off nt
	s_mov_b64 s[20:21], exec
	s_mov_b64 exec, 1
	global_atomic_add v250, v252, v251, s[16:17] sc0
	s_mov_b64 exec, s[20:21]
	v_mov_b32_e32 v158, 0
	s_waitcnt vmcnt(32)
	v_mul_f32_e32 v120, 0x43000000, v120
	s_waitcnt vmcnt(31)
	v_mul_f32_e32 v124, 0x43000000, v124
	v_med3_f32 v120, v120, s13, v149
	v_med3_f32 v124, v124, s13, v149
	v_cvt_pk_fp8_f32 v158, v120, v124
	s_waitcnt vmcnt(30)
	v_mul_f32_e32 v112, 0x43000000, v112
	s_waitcnt vmcnt(29)
	v_mul_f32_e32 v116, 0x43000000, v116
	v_med3_f32 v112, v112, s13, v149
	v_med3_f32 v116, v116, s13, v149
	v_cvt_pk_fp8_f32 v158, v112, v116 op_sel:[0,0,1]
	v_mul_f32_e32 v112, 0x43000000, v121
	v_mul_f32_e32 v116, 0x43000000, v125
	v_med3_f32 v112, v112, s13, v149
	v_med3_f32 v116, v116, s13, v149
	v_mov_b32_e32 v120, 0
	v_cvt_pk_fp8_f32 v120, v112, v116
	v_mul_f32_e32 v112, 0x43000000, v113
	v_mul_f32_e32 v113, 0x43000000, v117
	v_med3_f32 v112, v112, s13, v149
	v_med3_f32 v113, v113, s13, v149
	v_cvt_pk_fp8_f32 v120, v112, v113 op_sel:[0,0,1]
	v_mul_f32_e32 v112, 0x43000000, v122
	v_mul_f32_e32 v113, 0x43000000, v126
	v_med3_f32 v112, v112, s13, v149
	v_med3_f32 v113, v113, s13, v149
	v_mov_b32_e32 v116, 0
	v_cvt_pk_fp8_f32 v116, v112, v113
	v_mul_f32_e32 v112, 0x43000000, v114
	v_mul_f32_e32 v113, 0x43000000, v118
	v_med3_f32 v112, v112, s13, v149
	v_med3_f32 v113, v113, s13, v149
	v_cvt_pk_fp8_f32 v116, v112, v113 op_sel:[0,0,1]
	v_mul_f32_e32 v112, 0x43000000, v123
	v_mul_f32_e32 v113, 0x43000000, v127
	v_med3_f32 v112, v112, s13, v149
	v_med3_f32 v113, v113, s13, v149
	v_mov_b32_e32 v114, 0
	v_cvt_pk_fp8_f32 v114, v112, v113
	v_mul_f32_e32 v112, 0x43000000, v115
	v_mul_f32_e32 v113, 0x43000000, v119
	v_med3_f32 v112, v112, s13, v149
	v_med3_f32 v113, v113, s13, v149
	s_waitcnt vmcnt(28)
	v_mul_f32_e32 v104, 0x43000000, v104
	s_waitcnt vmcnt(27)
	v_mul_f32_e32 v108, 0x43000000, v108
	v_cvt_pk_fp8_f32 v114, v112, v113 op_sel:[0,0,1]
	v_med3_f32 v104, v104, s13, v149
	v_med3_f32 v108, v108, s13, v149
	v_mov_b32_e32 v112, 0
	v_cvt_pk_fp8_f32 v112, v104, v108
	s_waitcnt vmcnt(26)
	v_mul_f32_e32 v96, 0x43000000, v96
	s_waitcnt vmcnt(25)
	v_mul_f32_e32 v100, 0x43000000, v100
	v_med3_f32 v96, v96, s13, v149
	v_med3_f32 v100, v100, s13, v149
	v_cvt_pk_fp8_f32 v112, v96, v100 op_sel:[0,0,1]
	v_mul_f32_e32 v96, 0x43000000, v105
	v_mul_f32_e32 v100, 0x43000000, v109
	v_med3_f32 v96, v96, s13, v149
	v_med3_f32 v100, v100, s13, v149
	v_mov_b32_e32 v104, 0
	v_cvt_pk_fp8_f32 v104, v96, v100
	v_mul_f32_e32 v96, 0x43000000, v97
	v_mul_f32_e32 v97, 0x43000000, v101
	v_med3_f32 v96, v96, s13, v149
	v_med3_f32 v97, v97, s13, v149
	v_cvt_pk_fp8_f32 v104, v96, v97 op_sel:[0,0,1]
	v_mul_f32_e32 v96, 0x43000000, v106
	v_mul_f32_e32 v97, 0x43000000, v110
	v_med3_f32 v96, v96, s13, v149
	v_med3_f32 v97, v97, s13, v149
	v_mov_b32_e32 v100, 0
	v_cvt_pk_fp8_f32 v100, v96, v97
	v_mul_f32_e32 v96, 0x43000000, v98
	v_mul_f32_e32 v97, 0x43000000, v102
	v_med3_f32 v96, v96, s13, v149
	v_med3_f32 v97, v97, s13, v149
	v_cvt_pk_fp8_f32 v100, v96, v97 op_sel:[0,0,1]
	v_mul_f32_e32 v96, 0x43000000, v107
	v_mul_f32_e32 v97, 0x43000000, v111
	v_med3_f32 v96, v96, s13, v149
	v_med3_f32 v97, v97, s13, v149
	v_mov_b32_e32 v98, 0
	v_cvt_pk_fp8_f32 v98, v96, v97
	v_mul_f32_e32 v96, 0x43000000, v99
	v_mul_f32_e32 v97, 0x43000000, v103
	v_med3_f32 v96, v96, s13, v149
	v_med3_f32 v97, v97, s13, v149
	s_waitcnt vmcnt(24)
	v_mul_f32_e32 v88, 0x43000000, v88
	s_waitcnt vmcnt(23)
	v_mul_f32_e32 v92, 0x43000000, v92
	v_cvt_pk_fp8_f32 v98, v96, v97 op_sel:[0,0,1]
	v_med3_f32 v88, v88, s13, v149
	v_med3_f32 v92, v92, s13, v149
	v_mov_b32_e32 v96, 0
	v_cvt_pk_fp8_f32 v96, v88, v92
	s_waitcnt vmcnt(22)
	v_mul_f32_e32 v80, 0x43000000, v80
	s_waitcnt vmcnt(21)
	v_mul_f32_e32 v84, 0x43000000, v84
	v_med3_f32 v80, v80, s13, v149
	v_med3_f32 v84, v84, s13, v149
	v_cvt_pk_fp8_f32 v96, v80, v84 op_sel:[0,0,1]
	v_mul_f32_e32 v80, 0x43000000, v89
	v_mul_f32_e32 v84, 0x43000000, v93
	v_med3_f32 v80, v80, s13, v149
	v_med3_f32 v84, v84, s13, v149
	v_mov_b32_e32 v88, 0
	v_cvt_pk_fp8_f32 v88, v80, v84
	v_mul_f32_e32 v80, 0x43000000, v81
	v_mul_f32_e32 v81, 0x43000000, v85
	v_med3_f32 v80, v80, s13, v149
	v_med3_f32 v81, v81, s13, v149
	v_cvt_pk_fp8_f32 v88, v80, v81 op_sel:[0,0,1]
	v_mul_f32_e32 v80, 0x43000000, v90
	v_mul_f32_e32 v81, 0x43000000, v94
	v_med3_f32 v80, v80, s13, v149
	v_med3_f32 v81, v81, s13, v149
	v_mov_b32_e32 v84, 0
	v_cvt_pk_fp8_f32 v84, v80, v81
	v_mul_f32_e32 v80, 0x43000000, v82
	v_mul_f32_e32 v81, 0x43000000, v86
	v_med3_f32 v80, v80, s13, v149
	v_med3_f32 v81, v81, s13, v149
	v_cvt_pk_fp8_f32 v84, v80, v81 op_sel:[0,0,1]
	v_mul_f32_e32 v80, 0x43000000, v91
	v_mul_f32_e32 v81, 0x43000000, v95
	v_med3_f32 v80, v80, s13, v149
	v_med3_f32 v81, v81, s13, v149
	v_mov_b32_e32 v82, 0
	v_cvt_pk_fp8_f32 v82, v80, v81
	v_mul_f32_e32 v80, 0x43000000, v83
	v_mul_f32_e32 v81, 0x43000000, v87
	v_med3_f32 v80, v80, s13, v149
	v_med3_f32 v81, v81, s13, v149
	s_waitcnt vmcnt(20)
	v_mul_f32_e32 v72, 0x43000000, v72
	s_waitcnt vmcnt(19)
	v_mul_f32_e32 v76, 0x43000000, v76
	v_cvt_pk_fp8_f32 v82, v80, v81 op_sel:[0,0,1]
	v_med3_f32 v72, v72, s13, v149
	v_med3_f32 v76, v76, s13, v149
	v_mov_b32_e32 v80, 0
	v_cvt_pk_fp8_f32 v80, v72, v76
	s_waitcnt vmcnt(18)
	v_mul_f32_e32 v64, 0x43000000, v64
	s_waitcnt vmcnt(17)
	v_mul_f32_e32 v68, 0x43000000, v68
	v_med3_f32 v64, v64, s13, v149
	v_med3_f32 v68, v68, s13, v149
	v_cvt_pk_fp8_f32 v80, v64, v68 op_sel:[0,0,1]
	v_mul_f32_e32 v64, 0x43000000, v73
	v_mul_f32_e32 v68, 0x43000000, v77
	v_med3_f32 v64, v64, s13, v149
	v_med3_f32 v68, v68, s13, v149
	v_mov_b32_e32 v72, 0
	v_cvt_pk_fp8_f32 v72, v64, v68
	v_mul_f32_e32 v64, 0x43000000, v65
	v_mul_f32_e32 v65, 0x43000000, v69
	v_med3_f32 v64, v64, s13, v149
	v_med3_f32 v65, v65, s13, v149
	v_cvt_pk_fp8_f32 v72, v64, v65 op_sel:[0,0,1]
	v_mul_f32_e32 v64, 0x43000000, v74
	v_mul_f32_e32 v65, 0x43000000, v78
	v_med3_f32 v64, v64, s13, v149
	v_med3_f32 v65, v65, s13, v149
	v_mov_b32_e32 v68, 0
	v_cvt_pk_fp8_f32 v68, v64, v65
	v_mul_f32_e32 v64, 0x43000000, v66
	v_mul_f32_e32 v65, 0x43000000, v70
	v_med3_f32 v64, v64, s13, v149
	v_med3_f32 v65, v65, s13, v149
	v_cvt_pk_fp8_f32 v68, v64, v65 op_sel:[0,0,1]
	v_mul_f32_e32 v64, 0x43000000, v75
	v_mul_f32_e32 v65, 0x43000000, v79
	v_med3_f32 v64, v64, s13, v149
	v_med3_f32 v65, v65, s13, v149
	v_mov_b32_e32 v66, 0
	v_cvt_pk_fp8_f32 v66, v64, v65
	v_mul_f32_e32 v64, 0x43000000, v67
	v_mul_f32_e32 v65, 0x43000000, v71
	v_med3_f32 v64, v64, s13, v149
	v_med3_f32 v65, v65, s13, v149
	s_waitcnt vmcnt(16)
	v_mul_f32_e32 v56, 0x43000000, v56
	s_waitcnt vmcnt(15)
	v_mul_f32_e32 v60, 0x43000000, v60
	v_cvt_pk_fp8_f32 v66, v64, v65 op_sel:[0,0,1]
	v_med3_f32 v56, v56, s13, v149
	v_med3_f32 v60, v60, s13, v149
	v_mov_b32_e32 v64, 0
	v_cvt_pk_fp8_f32 v64, v56, v60
	s_waitcnt vmcnt(14)
	v_mul_f32_e32 v48, 0x43000000, v48
	s_waitcnt vmcnt(13)
	v_mul_f32_e32 v52, 0x43000000, v52
	v_med3_f32 v48, v48, s13, v149
	v_med3_f32 v52, v52, s13, v149
	v_cvt_pk_fp8_f32 v64, v48, v52 op_sel:[0,0,1]
	v_mul_f32_e32 v48, 0x43000000, v57
	v_mul_f32_e32 v52, 0x43000000, v61
	v_med3_f32 v48, v48, s13, v149
	v_med3_f32 v52, v52, s13, v149
	v_mov_b32_e32 v56, 0
	v_cvt_pk_fp8_f32 v56, v48, v52
	v_mul_f32_e32 v48, 0x43000000, v49
	v_mul_f32_e32 v49, 0x43000000, v53
	v_med3_f32 v48, v48, s13, v149
	v_med3_f32 v49, v49, s13, v149
	v_cvt_pk_fp8_f32 v56, v48, v49 op_sel:[0,0,1]
	v_mul_f32_e32 v48, 0x43000000, v58
	v_mul_f32_e32 v49, 0x43000000, v62
	v_med3_f32 v48, v48, s13, v149
	v_med3_f32 v49, v49, s13, v149
	v_mov_b32_e32 v52, 0
	v_cvt_pk_fp8_f32 v52, v48, v49
	v_mul_f32_e32 v48, 0x43000000, v50
	v_mul_f32_e32 v49, 0x43000000, v54
	v_med3_f32 v48, v48, s13, v149
	v_med3_f32 v49, v49, s13, v149
	v_cvt_pk_fp8_f32 v52, v48, v49 op_sel:[0,0,1]
	v_mul_f32_e32 v48, 0x43000000, v59
	v_mul_f32_e32 v49, 0x43000000, v63
	v_med3_f32 v48, v48, s13, v149
	v_med3_f32 v49, v49, s13, v149
	v_mov_b32_e32 v50, 0
	v_cvt_pk_fp8_f32 v50, v48, v49
	v_mul_f32_e32 v48, 0x43000000, v51
	v_mul_f32_e32 v49, 0x43000000, v55
	v_med3_f32 v48, v48, s13, v149
	v_med3_f32 v49, v49, s13, v149
	s_waitcnt vmcnt(12)
	v_mul_f32_e32 v40, 0x43000000, v40
	s_waitcnt vmcnt(11)
	v_mul_f32_e32 v44, 0x43000000, v44
	v_cvt_pk_fp8_f32 v50, v48, v49 op_sel:[0,0,1]
	v_med3_f32 v40, v40, s13, v149
	v_med3_f32 v44, v44, s13, v149
	v_mov_b32_e32 v48, 0
	v_cvt_pk_fp8_f32 v48, v40, v44
	s_waitcnt vmcnt(10)
	v_mul_f32_e32 v32, 0x43000000, v32
	s_waitcnt vmcnt(9)
	v_mul_f32_e32 v36, 0x43000000, v36
	v_med3_f32 v32, v32, s13, v149
	v_med3_f32 v36, v36, s13, v149
	v_cvt_pk_fp8_f32 v48, v32, v36 op_sel:[0,0,1]
	v_mul_f32_e32 v32, 0x43000000, v41
	v_mul_f32_e32 v36, 0x43000000, v45
	v_med3_f32 v32, v32, s13, v149
	v_med3_f32 v36, v36, s13, v149
	v_mov_b32_e32 v40, 0
	v_cvt_pk_fp8_f32 v40, v32, v36
	v_mul_f32_e32 v32, 0x43000000, v33
	v_mul_f32_e32 v33, 0x43000000, v37
	v_med3_f32 v32, v32, s13, v149
	v_med3_f32 v33, v33, s13, v149
	v_cvt_pk_fp8_f32 v40, v32, v33 op_sel:[0,0,1]
	v_mul_f32_e32 v32, 0x43000000, v42
	v_mul_f32_e32 v33, 0x43000000, v46
	v_med3_f32 v32, v32, s13, v149
	v_med3_f32 v33, v33, s13, v149
	v_mov_b32_e32 v36, 0
	v_cvt_pk_fp8_f32 v36, v32, v33
	v_mul_f32_e32 v32, 0x43000000, v34
	v_mul_f32_e32 v33, 0x43000000, v38
	v_med3_f32 v32, v32, s13, v149
	v_med3_f32 v33, v33, s13, v149
	v_cvt_pk_fp8_f32 v36, v32, v33 op_sel:[0,0,1]
	v_mul_f32_e32 v32, 0x43000000, v43
	v_mul_f32_e32 v33, 0x43000000, v47
	v_med3_f32 v32, v32, s13, v149
	v_med3_f32 v33, v33, s13, v149
	v_mov_b32_e32 v34, 0
	v_cvt_pk_fp8_f32 v34, v32, v33
	v_mul_f32_e32 v32, 0x43000000, v35
	v_mul_f32_e32 v33, 0x43000000, v39
	v_med3_f32 v32, v32, s13, v149
	v_med3_f32 v33, v33, s13, v149
	s_waitcnt vmcnt(8)
	v_mul_f32_e32 v24, 0x43000000, v24
	s_waitcnt vmcnt(7)
	v_mul_f32_e32 v28, 0x43000000, v28
	v_cvt_pk_fp8_f32 v34, v32, v33 op_sel:[0,0,1]
	v_med3_f32 v24, v24, s13, v149
	v_med3_f32 v28, v28, s13, v149
	v_mov_b32_e32 v32, 0
	v_cvt_pk_fp8_f32 v32, v24, v28
	s_waitcnt vmcnt(6)
	v_mul_f32_e32 v16, 0x43000000, v16
	s_waitcnt vmcnt(5)
	v_mul_f32_e32 v20, 0x43000000, v20
	v_med3_f32 v16, v16, s13, v149
	v_med3_f32 v20, v20, s13, v149
	v_cvt_pk_fp8_f32 v32, v16, v20 op_sel:[0,0,1]
	v_mul_f32_e32 v16, 0x43000000, v25
	v_mul_f32_e32 v20, 0x43000000, v29
	v_med3_f32 v16, v16, s13, v149
	v_med3_f32 v20, v20, s13, v149
	v_mov_b32_e32 v24, 0
	v_cvt_pk_fp8_f32 v24, v16, v20
	v_mul_f32_e32 v16, 0x43000000, v17
	v_mul_f32_e32 v17, 0x43000000, v21
	v_med3_f32 v16, v16, s13, v149
	v_med3_f32 v17, v17, s13, v149
	v_cvt_pk_fp8_f32 v24, v16, v17 op_sel:[0,0,1]
	v_mul_f32_e32 v16, 0x43000000, v26
	v_mul_f32_e32 v17, 0x43000000, v30
	v_med3_f32 v16, v16, s13, v149
	v_med3_f32 v17, v17, s13, v149
	v_mov_b32_e32 v20, 0
	v_cvt_pk_fp8_f32 v20, v16, v17
	v_mul_f32_e32 v16, 0x43000000, v18
	v_mul_f32_e32 v17, 0x43000000, v22
	v_med3_f32 v16, v16, s13, v149
	v_med3_f32 v17, v17, s13, v149
	v_cvt_pk_fp8_f32 v20, v16, v17 op_sel:[0,0,1]
	v_mul_f32_e32 v16, 0x43000000, v27
	v_mul_f32_e32 v17, 0x43000000, v31
	v_med3_f32 v16, v16, s13, v149
	v_med3_f32 v17, v17, s13, v149
	v_mov_b32_e32 v18, 0
	v_cvt_pk_fp8_f32 v18, v16, v17
	v_mul_f32_e32 v16, 0x43000000, v19
	v_mul_f32_e32 v17, 0x43000000, v23
	v_med3_f32 v16, v16, s13, v149
	v_med3_f32 v17, v17, s13, v149
	s_waitcnt vmcnt(4)
	v_mul_f32_e32 v8, 0x43000000, v8
	s_waitcnt vmcnt(3)
	v_mul_f32_e32 v12, 0x43000000, v12
	v_cvt_pk_fp8_f32 v18, v16, v17 op_sel:[0,0,1]
	v_med3_f32 v8, v8, s13, v149
	v_med3_f32 v12, v12, s13, v149
	v_mov_b32_e32 v16, 0
	v_cvt_pk_fp8_f32 v16, v8, v12
	s_waitcnt vmcnt(2)
	v_mul_f32_e32 v0, 0x43000000, v0
	s_waitcnt vmcnt(0)
	v_readfirstlane_b32 s22, v250
	v_mul_f32_e32 v4, 0x43000000, v4
	v_med3_f32 v0, v0, s13, v149
	v_med3_f32 v4, v4, s13, v149
	v_cvt_pk_fp8_f32 v16, v0, v4 op_sel:[0,0,1]
	v_mul_f32_e32 v0, 0x43000000, v9
	v_mul_f32_e32 v4, 0x43000000, v13
	v_med3_f32 v0, v0, s13, v149
	v_med3_f32 v4, v4, s13, v149
	v_mov_b32_e32 v8, 0
	v_cvt_pk_fp8_f32 v8, v0, v4
	v_mul_f32_e32 v0, 0x43000000, v1
	v_mul_f32_e32 v1, 0x43000000, v5
	v_med3_f32 v0, v0, s13, v149
	v_med3_f32 v1, v1, s13, v149
	v_cvt_pk_fp8_f32 v8, v0, v1 op_sel:[0,0,1]
	v_mul_f32_e32 v0, 0x43000000, v10
	v_mul_f32_e32 v1, 0x43000000, v14
	v_med3_f32 v0, v0, s13, v149
	v_med3_f32 v1, v1, s13, v149
	v_mov_b32_e32 v4, 0
	v_cvt_pk_fp8_f32 v4, v0, v1
	v_mul_f32_e32 v0, 0x43000000, v2
	v_mul_f32_e32 v1, 0x43000000, v6
	v_med3_f32 v0, v0, s13, v149
	v_med3_f32 v1, v1, s13, v149
	v_cvt_pk_fp8_f32 v4, v0, v1 op_sel:[0,0,1]
	v_mul_f32_e32 v0, 0x43000000, v11
	v_mul_f32_e32 v1, 0x43000000, v15
	v_med3_f32 v0, v0, s13, v149
	v_med3_f32 v1, v1, s13, v149
	v_mov_b32_e32 v2, 0
	v_cvt_pk_fp8_f32 v2, v0, v1
	v_mul_f32_e32 v0, 0x43000000, v3
	v_mul_f32_e32 v1, 0x43000000, v7
	v_med3_f32 v0, v0, s13, v149
	v_med3_f32 v1, v1, s13, v149
	v_cvt_pk_fp8_f32 v2, v0, v1 op_sel:[0,0,1]
	ds_write2_b32 v150, v158, v120 offset1:32
	ds_write2_b32 v150, v116, v114 offset0:64 offset1:96
	ds_write2_b32 v151, v112, v104 offset1:32
	ds_write2_b32 v151, v100, v98 offset0:64 offset1:96
	ds_write2_b32 v152, v96, v88 offset1:32
	ds_write2_b32 v152, v84, v82 offset0:64 offset1:96
	ds_write2_b32 v153, v80, v72 offset1:32
	ds_write2_b32 v153, v68, v66 offset0:64 offset1:96
	ds_write2_b32 v154, v64, v56 offset1:32
	ds_write2_b32 v154, v52, v50 offset0:64 offset1:96
	ds_write2_b32 v155, v48, v40 offset1:32
	ds_write2_b32 v155, v36, v34 offset0:64 offset1:96
	ds_write2_b32 v156, v32, v24 offset1:32
	ds_write2_b32 v156, v20, v18 offset0:64 offset1:96
	ds_write2_b32 v157, v16, v8 offset1:32
	ds_write2_b32 v157, v4, v2 offset0:64 offset1:96
	s_waitcnt lgkmcnt(0)
	ds_read_b128 v[0:3], v134
	v_lshl_add_u64 v[4:5], v[130:131], 0, s[4:5]
	v_add_u32_e32 v6, s2, v133
	v_mad_i64_i32 v[6:7], s[4:5], v6, s14, v[4:5]
	s_waitcnt lgkmcnt(0)
	global_store_dwordx4 v[6:7], v[0:3], off
	ds_read_b128 v[0:3], v136
	v_add_u32_e32 v6, s2, v135
	v_mad_i64_i32 v[6:7], s[4:5], v6, s14, v[4:5]
	s_waitcnt lgkmcnt(0)
	global_store_dwordx4 v[6:7], v[0:3], off
	ds_read_b128 v[0:3], v138
	v_add_u32_e32 v6, s2, v137
	v_mad_i64_i32 v[6:7], s[4:5], v6, s14, v[4:5]
	s_waitcnt lgkmcnt(0)
	global_store_dwordx4 v[6:7], v[0:3], off
	ds_read_b128 v[0:3], v140
	v_add_u32_e32 v6, s2, v139
	v_mad_i64_i32 v[6:7], s[4:5], v6, s14, v[4:5]
	s_waitcnt lgkmcnt(0)
	global_store_dwordx4 v[6:7], v[0:3], off
	ds_read_b128 v[0:3], v142
	v_add_u32_e32 v6, s2, v141
	v_mad_i64_i32 v[6:7], s[4:5], v6, s14, v[4:5]
	s_waitcnt lgkmcnt(0)
	global_store_dwordx4 v[6:7], v[0:3], off
	ds_read_b128 v[0:3], v144
	v_add_u32_e32 v6, s2, v143
	v_mad_i64_i32 v[6:7], s[4:5], v6, s14, v[4:5]
	s_waitcnt lgkmcnt(0)
	global_store_dwordx4 v[6:7], v[0:3], off
	ds_read_b128 v[0:3], v146
	v_add_u32_e32 v6, s2, v145
	v_mad_i64_i32 v[6:7], s[4:5], v6, s14, v[4:5]
	s_waitcnt lgkmcnt(0)
	global_store_dwordx4 v[6:7], v[0:3], off
	ds_read_b128 v[0:3], v148
	v_add_u32_e32 v6, s2, v147
	v_mad_i64_i32 v[4:5], s[4:5], v6, s14, v[4:5]
	s_waitcnt lgkmcnt(0)
	global_store_dwordx4 v[4:5], v[0:3], off
	s_waitcnt lgkmcnt(0)
	s_mov_b32 s3, s22
	s_lshl_b32 s7, s3, 1
	s_lshl_b32 s11, s3, 6
	s_sub_u32 s23, s23, 1
	s_cmp_eq_u32 s23, 0
	s_cbranch_scc1 .LBB0_233
	s_cmpk_lt_i32 s3, 0x1580
	s_cbranch_scc1 .LBB0_232

.LBB0_1572:
	s_abs_i32 s0, s33
	v_cvt_f32_u32_e32 v0, s0
	s_sub_i32 s1, 0, s0
	v_rcp_iflag_f32_e32 v0, v0
	s_nop 0
	v_mul_f32_e32 v0, 0x4f7ffffe, v0
	v_cvt_u32_f32_e32 v0, v0
	s_nop 0
	v_readfirstlane_b32 s2, v0
	s_mul_i32 s1, s1, s2
	s_mul_hi_u32 s1, s2, s1
	s_add_i32 s2, s2, s1
	s_mul_hi_u32 s1, s2, 0xb6c
	s_mul_i32 s1, s1, s0
	s_sub_i32 s1, 0xb6c, s1
	s_sub_i32 s2, s1, s0
	s_cmp_ge_u32 s1, s0
	s_cselect_b32 s1, s2, s1
	s_sub_i32 s2, s1, s0
	s_cmp_ge_u32 s1, s0
	s_cselect_b32 s0, s2, s1
	s_sub_i32 s1, s95, s0
	s_cmp_lt_i32 s1, 0
	s_nop 0
	s_lshl_b32 s1, s1, 3
	v_readlane_b32 s2, v254, 16
	s_add_i32 s2, s1, s2
	s_cmpk_gt_i32 s2, 0x157f
	s_nop 0
	v_lshlrev_b32_e32 v1, 2, v141
	s_waitcnt vmcnt(15)
	v_ashrrev_i32_e32 v65, 3, v141
	v_bitop3_b32 v12, v65, 28, v1 bitop3:0x48
	v_add_u32_e32 v67, 8, v65
	v_readlane_b32 s5, v254, 17
	v_lshlrev_b32_e32 v11, 7, v65
	v_lshlrev_b32_e32 v12, 2, v12
	v_bitop3_b32 v13, v67, 28, v1 bitop3:0x48
	v_add3_u32 v66, s5, v11, v12
	v_lshlrev_b32_e32 v11, 7, v67
	v_lshlrev_b32_e32 v13, 2, v13
	s_waitcnt vmcnt(14)
	v_add_u32_e32 v69, 16, v65
	v_add3_u32 v68, s5, v11, v13
	v_bitop3_b32 v13, v69, 28, v1 bitop3:0x48
	v_lshlrev_b32_e32 v11, 7, v69
	v_lshlrev_b32_e32 v13, 2, v13
	v_add_u32_e32 v71, 24, v65
	v_add3_u32 v70, s5, v11, v13
	v_bitop3_b32 v13, v71, 28, v1 bitop3:0x48
	v_lshlrev_b32_e32 v11, 7, v71
	v_lshlrev_b32_e32 v13, 2, v13
	s_waitcnt vmcnt(13)
	v_add_u32_e32 v73, 32, v65
	v_add3_u32 v72, s5, v11, v13
	v_lshlrev_b32_e32 v11, 7, v73
	v_add_u32_e32 v75, 40, v65
	v_ashrrev_i32_e32 v0, 4, v141
	v_add3_u32 v74, s5, v11, v12
	v_bitop3_b32 v12, v75, 28, v1 bitop3:0x48
	v_lshlrev_b32_e32 v64, 2, v0
	v_lshlrev_b32_e32 v3, 4, v141
	v_lshlrev_b32_e32 v11, 7, v75
	v_lshlrev_b32_e32 v12, 2, v12
	s_waitcnt vmcnt(12)
	v_add_u32_e32 v77, 48, v65
	v_add_u32_e32 v2, s5, v64
	v_and_b32_e32 v44, 0x70, v3
	s_movk_i32 s4, 0x50
	v_add3_u32 v76, s5, v11, v12
	v_bitop3_b32 v12, v77, 28, v1 bitop3:0x48
	v_add_u32_e32 v79, 56, v65
	s_sub_i32 s1, s33, s0
	v_and_b32_e32 v0, 60, v1
	s_movk_i32 s3, 0x70
	v_xad_u32 v9, v44, s4, v2
	s_movk_i32 s4, 0x60
	v_readlane_b32 s6, v254, 29
	v_lshlrev_b32_e32 v11, 7, v77
	v_lshlrev_b32_e32 v12, 2, v12
	v_bitop3_b32 v1, v79, 28, v1 bitop3:0x48
	v_mov_b32_e32 v45, 0
	v_add_u32_e32 v3, v2, v44
	v_lshlrev_b32_e32 v4, 7, v0
	v_xad_u32 v5, v44, 16, v2
	v_xad_u32 v6, v44, 32, v2
	v_xad_u32 v7, v44, 48, v2
	v_xad_u32 v8, v44, 64, v2
	v_xad_u32 v10, v44, s4, v2
	v_xad_u32 v2, v44, s3, v2
	v_readlane_b32 s7, v254, 30
	v_add3_u32 v78, s5, v11, v12
	v_lshlrev_b32_e32 v11, 7, v79
	v_lshlrev_b32_e32 v1, 2, v1
	s_lshl_b32 s3, s1, 3
	s_lshl_b32 s1, s33, 4
	s_lshl_b32 s4, s0, 4
	s_lshl_b32 s0, s0, 9
	v_lshl_add_u64 v[46:47], s[6:7], 0, v[44:45]
	s_waitcnt vmcnt(11)
	v_add3_u32 v80, s5, v11, v1
	s_lshl_b32 s6, s2, 1
	s_sub_i32 s7, s1, s4
	s_lshl_b32 s8, s2, 6
	s_sub_i32 s9, s44, s0
	s_mov_b32 s1, 0
	v_lshlrev_b32_e32 v44, 2, v0
	s_mov_b32 s10, 0xc3e00000
	v_mov_b32_e32 v81, 0x43e00000
	v_add_u32_e32 v82, v3, v4
	v_add_u32_e32 v83, v5, v4
	s_waitcnt vmcnt(10)
	v_add_u32_e32 v84, v6, v4
	v_add_u32_e32 v85, v7, v4
	v_add_u32_e32 v86, v8, v4
	v_add_u32_e32 v87, v9, v4
	s_waitcnt vmcnt(9)
	v_add_u32_e32 v88, v10, v4
	v_add_u32_e32 v89, v2, v4
	s_movk_i32 s11, 0x2b00
	s_add_u32 s22, s34, 0x8040
	s_addc_u32 s23, s35, 0
	v_mov_b32_e32 v251, 1
	v_mov_b32_e32 v252, 0
	s_movk_i32 s24, 0x60
	s_mov_b64 s[26:27], exec
	s_mov_b64 exec, 1
	global_atomic_add v250, v252, v251, s[22:23] sc0
	s_mov_b64 exec, s[26:27]
	s_waitcnt vmcnt(0)
	v_readfirstlane_b32 s2, v250
	s_nop 3
	s_cmpk_gt_i32 s2, 0x157f
	s_cbranch_scc1 .LBB0_1576
	s_lshl_b32 s6, s2, 1
	s_lshl_b32 s8, s2, 6
.LBB0_1575:
	s_and_b32 s4, s6, 0xffffff80
	v_add_u32_e32 v0, s4, v64
	v_ashrrev_i32_e32 v1, 31, v0
	s_and_b32 s12, s8, 0xfc0
	v_lshlrev_b64 v[0:1], 14, v[0:1]
	s_lshl_b32 s0, s12, 2
	v_lshl_add_u64 v[0:1], s[56:57], 0, v[0:1]
	s_ashr_i32 s5, s4, 31
	v_lshl_add_u64 v[0:1], v[0:1], 0, s[0:1]
	v_add_u32_e32 v4, s12, v65
	v_add_u32_e32 v5, s12, v67
	v_add_u32_e32 v6, s12, v69
	v_add_u32_e32 v7, s12, v71
	v_add_u32_e32 v8, s12, v73
	v_add_u32_e32 v9, s12, v75
	v_add_u32_e32 v10, s12, v77
	v_add_u32_e32 v11, s12, v79
	v_lshl_add_u64 v[2:3], v[46:47], 0, s[4:5]
	v_lshl_add_u64 v[0:1], v[0:1], 0, v[44:45]
	v_mad_i64_i32 v[48:49], s[4:5], v4, s11, v[2:3]
	v_mad_i64_i32 v[50:51], s[4:5], v5, s11, v[2:3]
	v_mad_i64_i32 v[52:53], s[4:5], v6, s11, v[2:3]
	v_mad_i64_i32 v[54:55], s[4:5], v7, s11, v[2:3]
	v_mad_i64_i32 v[56:57], s[4:5], v8, s11, v[2:3]
	v_mad_i64_i32 v[58:59], s[4:5], v9, s11, v[2:3]
	v_mad_i64_i32 v[60:61], s[4:5], v10, s11, v[2:3]
	v_mad_i64_i32 v[62:63], s[4:5], v11, s11, v[2:3]
	v_add_co_u32_e32 v2, vcc, 0x4000, v0
	global_load_dwordx4 v[122:125], v[0:1], off nt
	s_nop 0
	v_addc_co_u32_e32 v3, vcc, 0, v1, vcc
	v_add_co_u32_e32 v4, vcc, 0x8000, v0
	s_nop 1
	global_load_dwordx4 v[126:129], v[2:3], off nt
	s_nop 0
	v_addc_co_u32_e32 v5, vcc, 0, v1, vcc
	v_add_co_u32_e32 v2, vcc, 0xc000, v0
	s_nop 1
	s_nop 0
	v_addc_co_u32_e32 v3, vcc, 0, v1, vcc
	v_add_co_u32_e32 v6, vcc, 0x40000, v0
	s_nop 1
	global_load_dwordx4 v[130:133], v[4:5], off nt
	global_load_dwordx4 v[134:137], v[2:3], off nt
	v_addc_co_u32_e32 v7, vcc, 0, v1, vcc
	v_add_co_u32_e32 v2, vcc, 0x44000, v0
	s_nop 1
	v_addc_co_u32_e32 v3, vcc, 0, v1, vcc
	v_add_co_u32_e32 v4, vcc, 0x48000, v0
	s_nop 1
	global_load_dwordx4 v[138:141], v[6:7], off nt
	global_load_dwordx4 v[142:145], v[2:3], off nt
	v_addc_co_u32_e32 v5, vcc, 0, v1, vcc
	v_add_co_u32_e32 v2, vcc, 0x4c000, v0
	s_nop 1
	s_nop 0
	v_addc_co_u32_e32 v3, vcc, 0, v1, vcc
	v_add_co_u32_e32 v6, vcc, 0x80000, v0
	s_nop 1
	global_load_dwordx4 v[146:149], v[4:5], off nt
	global_load_dwordx4 v[150:153], v[2:3], off nt
	v_addc_co_u32_e32 v7, vcc, 0, v1, vcc
	v_add_co_u32_e32 v2, vcc, 0x84000, v0
	s_nop 1
	v_addc_co_u32_e32 v3, vcc, 0, v1, vcc
	v_add_co_u32_e32 v4, vcc, 0x88000, v0
	s_nop 1
	global_load_dwordx4 v[154:157], v[6:7], off nt
	global_load_dwordx4 v[158:161], v[2:3], off nt
	v_addc_co_u32_e32 v5, vcc, 0, v1, vcc
	v_add_co_u32_e32 v2, vcc, 0x8c000, v0
	s_nop 1
	s_nop 0
	v_addc_co_u32_e32 v3, vcc, 0, v1, vcc
	v_add_co_u32_e32 v6, vcc, 0xc0000, v0
	s_nop 1
	global_load_dwordx4 v[162:165], v[4:5], off nt
	global_load_dwordx4 v[166:169], v[2:3], off nt
	v_addc_co_u32_e32 v7, vcc, 0, v1, vcc
	v_add_co_u32_e32 v2, vcc, 0xc4000, v0
	s_nop 1
	s_nop 0
	v_addc_co_u32_e32 v3, vcc, 0, v1, vcc
	v_add_co_u32_e32 v4, vcc, 0xc8000, v0
	s_nop 1
	global_load_dwordx4 v[170:173], v[6:7], off nt
	global_load_dwordx4 v[174:177], v[2:3], off nt
	v_addc_co_u32_e32 v5, vcc, 0, v1, vcc
	v_add_co_u32_e32 v2, vcc, 0xcc000, v0
	s_nop 1
	v_addc_co_u32_e32 v3, vcc, 0, v1, vcc
	v_add_co_u32_e32 v6, vcc, 0x100000, v0
	s_nop 1
	global_load_dwordx4 v[178:181], v[4:5], off nt
	global_load_dwordx4 v[182:185], v[2:3], off nt
	v_addc_co_u32_e32 v7, vcc, 0, v1, vcc
	v_add_co_u32_e32 v2, vcc, 0x104000, v0
	s_nop 1
	v_addc_co_u32_e32 v3, vcc, 0, v1, vcc
	v_add_co_u32_e32 v4, vcc, 0x108000, v0
	s_nop 1
	global_load_dwordx4 v[186:189], v[6:7], off nt
	global_load_dwordx4 v[190:193], v[2:3], off nt
	v_addc_co_u32_e32 v5, vcc, 0, v1, vcc
	v_add_co_u32_e32 v2, vcc, 0x10c000, v0
	s_nop 1
	s_nop 0
	v_addc_co_u32_e32 v3, vcc, 0, v1, vcc
	v_add_co_u32_e32 v6, vcc, 0x140000, v0
	s_nop 1
	global_load_dwordx4 v[194:197], v[4:5], off nt
	global_load_dwordx4 v[198:201], v[2:3], off nt
	v_addc_co_u32_e32 v7, vcc, 0, v1, vcc
	v_add_co_u32_e32 v2, vcc, 0x144000, v0
	s_nop 1
	v_addc_co_u32_e32 v3, vcc, 0, v1, vcc
	v_add_co_u32_e32 v4, vcc, 0x148000, v0
	s_nop 1
	global_load_dwordx4 v[202:205], v[6:7], off nt
	global_load_dwordx4 v[40:43], v[2:3], off nt
	v_addc_co_u32_e32 v5, vcc, 0, v1, vcc
	v_add_co_u32_e32 v2, vcc, 0x14c000, v0
	s_nop 1
	s_nop 0
	v_addc_co_u32_e32 v3, vcc, 0, v1, vcc
	v_add_co_u32_e32 v6, vcc, 0x180000, v0
	s_nop 1
	global_load_dwordx4 v[36:39], v[4:5], off nt
	global_load_dwordx4 v[32:35], v[2:3], off nt
	v_addc_co_u32_e32 v7, vcc, 0, v1, vcc
	v_add_co_u32_e32 v2, vcc, 0x184000, v0
	s_nop 1
	s_nop 0
	v_addc_co_u32_e32 v3, vcc, 0, v1, vcc
	v_add_co_u32_e32 v4, vcc, 0x188000, v0
	s_nop 1
	global_load_dwordx4 v[28:31], v[6:7], off nt
	global_load_dwordx4 v[24:27], v[2:3], off nt
	v_addc_co_u32_e32 v5, vcc, 0, v1, vcc
	v_add_co_u32_e32 v2, vcc, 0x18c000, v0
	s_nop 1
	s_nop 0
	v_addc_co_u32_e32 v3, vcc, 0, v1, vcc
	v_add_co_u32_e32 v6, vcc, 0x1c0000, v0
	s_nop 1
	global_load_dwordx4 v[20:23], v[4:5], off nt
	global_load_dwordx4 v[16:19], v[2:3], off nt
	v_addc_co_u32_e32 v7, vcc, 0, v1, vcc
	v_add_co_u32_e32 v2, vcc, 0x1c4000, v0
	s_nop 1
	s_nop 0
	v_addc_co_u32_e32 v3, vcc, 0, v1, vcc
	v_add_co_u32_e32 v4, vcc, 0x1c8000, v0
	s_nop 1
	global_load_dwordx4 v[12:15], v[6:7], off nt
	global_load_dwordx4 v[8:11], v[2:3], off nt
	v_addc_co_u32_e32 v5, vcc, 0, v1, vcc
	v_add_co_u32_e32 v0, vcc, 0x1cc000, v0
	s_nop 1
	s_nop 0
	v_addc_co_u32_e32 v1, vcc, 0, v1, vcc
	global_load_dwordx4 v[4:7], v[4:5], off nt
	s_nop 0
	global_load_dwordx4 v[0:3], v[0:1], off nt
	s_mov_b64 s[26:27], exec
	s_mov_b64 exec, 1
	global_atomic_add v250, v252, v251, s[22:23] sc0
	s_mov_b64 exec, s[26:27]
	v_mov_b32_e32 v90, 0
	v_mov_b32_e32 v92, 0
	v_mov_b32_e32 v95, 0
	v_mov_b32_e32 v100, 0
	v_mov_b32_e32 v91, 0
	v_mov_b32_e32 v94, 0
	v_mov_b32_e32 v104, 0
	s_waitcnt vmcnt(32)
	v_mul_f32_e32 v122, 0x43000000, v122
	v_mul_f32_e32 v123, 0x43000000, v123
	s_waitcnt vmcnt(31)
	v_mul_f32_e32 v126, 0x43000000, v126
	v_mul_f32_e32 v127, 0x43000000, v127
	v_mul_f32_e32 v124, 0x43000000, v124
	v_mul_f32_e32 v125, 0x43000000, v125
	v_med3_f32 v122, v122, s10, v81
	v_med3_f32 v123, v123, s10, v81
	v_mul_f32_e32 v128, 0x43000000, v128
	v_mul_f32_e32 v129, 0x43000000, v129
	v_med3_f32 v126, v126, s10, v81
	v_med3_f32 v127, v127, s10, v81
	v_med3_f32 v124, v124, s10, v81
	v_med3_f32 v125, v125, s10, v81
	v_med3_f32 v128, v128, s10, v81
	v_med3_f32 v129, v129, s10, v81
	v_cvt_pk_fp8_f32 v90, v122, v126
	v_cvt_pk_fp8_f32 v92, v123, v127
	s_waitcnt vmcnt(30)
	v_mul_f32_e32 v130, 0x43000000, v130
	v_mul_f32_e32 v131, 0x43000000, v131
	v_mul_f32_e32 v133, 0x43000000, v133
	v_cvt_pk_fp8_f32 v95, v124, v128
	v_cvt_pk_fp8_f32 v100, v125, v129
	v_mul_f32_e32 v132, 0x43000000, v132
	v_med3_f32 v122, v130, s10, v81
	s_waitcnt vmcnt(29)
	v_mul_f32_e32 v126, 0x43000000, v134
	v_med3_f32 v123, v131, s10, v81
	v_mul_f32_e32 v127, 0x43000000, v135
	v_med3_f32 v125, v133, s10, v81
	v_mul_f32_e32 v129, 0x43000000, v137
	s_waitcnt vmcnt(28)
	v_mul_f32_e32 v130, 0x43000000, v138
	v_mul_f32_e32 v131, 0x43000000, v139
	v_mul_f32_e32 v133, 0x43000000, v141
	s_waitcnt vmcnt(27)
	v_mul_f32_e32 v134, 0x43000000, v142
	v_mul_f32_e32 v135, 0x43000000, v143
	v_mul_f32_e32 v137, 0x43000000, v145
	v_med3_f32 v124, v132, s10, v81
	v_mul_f32_e32 v128, 0x43000000, v136
	v_med3_f32 v126, v126, s10, v81
	v_med3_f32 v127, v127, s10, v81
	v_mul_f32_e32 v132, 0x43000000, v140
	v_med3_f32 v130, v130, s10, v81
	v_med3_f32 v131, v131, s10, v81
	v_mul_f32_e32 v136, 0x43000000, v144
	v_med3_f32 v133, v133, s10, v81
	v_med3_f32 v134, v134, s10, v81
	v_med3_f32 v135, v135, s10, v81
	v_med3_f32 v137, v137, s10, v81
	v_mov_b32_e32 v98, 0
	v_med3_f32 v128, v128, s10, v81
	v_med3_f32 v129, v129, s10, v81
	v_med3_f32 v132, v132, s10, v81
	v_med3_f32 v136, v136, s10, v81
	v_cvt_pk_fp8_f32 v90, v122, v126 op_sel:[0,0,1]
	v_cvt_pk_fp8_f32 v92, v123, v127 op_sel:[0,0,1]
	v_cvt_pk_fp8_f32 v91, v130, v134
	v_cvt_pk_fp8_f32 v94, v131, v135
	v_cvt_pk_fp8_f32 v104, v133, v137
	s_waitcnt vmcnt(24)
	v_mul_f32_e32 v130, 0x43000000, v154
	v_mul_f32_e32 v131, 0x43000000, v155
	s_waitcnt vmcnt(23)
	v_mul_f32_e32 v134, 0x43000000, v158
	v_mul_f32_e32 v135, 0x43000000, v159
	v_mov_b32_e32 v93, 0
	v_mov_b32_e32 v97, 0
	v_cvt_pk_fp8_f32 v95, v124, v128 op_sel:[0,0,1]
	v_cvt_pk_fp8_f32 v100, v125, v129 op_sel:[0,0,1]
	v_cvt_pk_fp8_f32 v98, v132, v136
	v_mul_f32_e32 v132, 0x43000000, v156
	v_mul_f32_e32 v133, 0x43000000, v157
	v_med3_f32 v130, v130, s10, v81
	v_med3_f32 v131, v131, s10, v81
	v_mul_f32_e32 v136, 0x43000000, v160
	v_mul_f32_e32 v137, 0x43000000, v161
	v_med3_f32 v134, v134, s10, v81
	v_med3_f32 v135, v135, s10, v81
	v_mov_b32_e32 v102, 0
	v_mov_b32_e32 v107, 0
	v_mul_f32_e32 v138, 0x43000000, v146
	v_mul_f32_e32 v139, 0x43000000, v147
	v_mul_f32_e32 v141, 0x43000000, v149
	v_mul_f32_e32 v123, 0x43000000, v150
	v_mul_f32_e32 v125, 0x43000000, v151
	v_mul_f32_e32 v129, 0x43000000, v153
	v_med3_f32 v132, v132, s10, v81
	v_med3_f32 v133, v133, s10, v81
	v_med3_f32 v136, v136, s10, v81
	v_med3_f32 v137, v137, s10, v81
	v_cvt_pk_fp8_f32 v93, v130, v134
	v_cvt_pk_fp8_f32 v97, v131, v135
	v_mul_f32_e32 v140, 0x43000000, v148
	v_med3_f32 v122, v138, s10, v81
	v_med3_f32 v124, v139, s10, v81
	v_mul_f32_e32 v127, 0x43000000, v152
	v_med3_f32 v128, v141, s10, v81
	v_med3_f32 v123, v123, s10, v81
	v_med3_f32 v125, v125, s10, v81
	v_med3_f32 v129, v129, s10, v81
	v_cvt_pk_fp8_f32 v102, v132, v136
	v_cvt_pk_fp8_f32 v107, v133, v137
	v_med3_f32 v126, v140, s10, v81
	v_med3_f32 v127, v127, s10, v81
	s_waitcnt vmcnt(22)
	v_mul_f32_e32 v138, 0x43000000, v162
	v_mul_f32_e32 v139, 0x43000000, v163
	ds_write2_b32 v82, v90, v92 offset1:32
	ds_write2_b32 v82, v95, v100 offset0:64 offset1:96
	v_cvt_pk_fp8_f32 v91, v122, v123 op_sel:[0,0,1]
	v_cvt_pk_fp8_f32 v94, v124, v125 op_sel:[0,0,1]
	v_cvt_pk_fp8_f32 v104, v128, v129 op_sel:[0,0,1]
	s_waitcnt vmcnt(21)
	v_mul_f32_e32 v92, 0x43000000, v166
	v_mul_f32_e32 v100, 0x43000000, v167
	s_waitcnt vmcnt(20)
	v_mul_f32_e32 v129, 0x43000000, v173
	s_waitcnt vmcnt(19)
	v_mul_f32_e32 v133, 0x43000000, v177
	v_mov_b32_e32 v110, 0
	v_mul_f32_e32 v140, 0x43000000, v164
	v_mul_f32_e32 v141, 0x43000000, v165
	v_cvt_pk_fp8_f32 v98, v126, v127 op_sel:[0,0,1]
	v_med3_f32 v90, v138, s10, v81
	v_med3_f32 v95, v139, s10, v81
	v_mul_f32_e32 v123, 0x43000000, v168
	v_mul_f32_e32 v125, 0x43000000, v169
	v_med3_f32 v92, v92, s10, v81
	v_med3_f32 v100, v100, s10, v81
	v_med3_f32 v129, v129, s10, v81
	v_med3_f32 v133, v133, s10, v81
	v_med3_f32 v122, v140, s10, v81
	v_med3_f32 v124, v141, s10, v81
	v_med3_f32 v123, v123, s10, v81
	v_med3_f32 v125, v125, s10, v81
	v_cvt_pk_fp8_f32 v93, v90, v92 op_sel:[0,0,1]
	v_cvt_pk_fp8_f32 v97, v95, v100 op_sel:[0,0,1]
	v_cvt_pk_fp8_f32 v110, v129, v133
	v_cvt_pk_fp8_f32 v102, v122, v123 op_sel:[0,0,1]
	v_cvt_pk_fp8_f32 v107, v124, v125 op_sel:[0,0,1]
	v_mul_f32_e32 v126, 0x43000000, v170
	v_mul_f32_e32 v127, 0x43000000, v171
	v_mul_f32_e32 v130, 0x43000000, v174
	v_mul_f32_e32 v131, 0x43000000, v175
	s_waitcnt vmcnt(18)
	v_mul_f32_e32 v137, 0x43000000, v181
	ds_write2_b32 v83, v91, v94 offset1:32
	ds_write2_b32 v83, v98, v104 offset0:64 offset1:96
	s_waitcnt vmcnt(17)
	v_mul_f32_e32 v104, 0x43000000, v185
	v_mov_b32_e32 v96, 0
	v_mov_b32_e32 v101, 0
	v_mul_f32_e32 v128, 0x43000000, v172
	v_med3_f32 v126, v126, s10, v81
	v_med3_f32 v127, v127, s10, v81
	v_mul_f32_e32 v132, 0x43000000, v176
	v_med3_f32 v130, v130, s10, v81
	v_med3_f32 v131, v131, s10, v81
	v_med3_f32 v100, v137, s10, v81
	v_med3_f32 v104, v104, s10, v81
	v_mov_b32_e32 v106, 0
	v_med3_f32 v128, v128, s10, v81
	v_med3_f32 v132, v132, s10, v81
	v_cvt_pk_fp8_f32 v96, v126, v130
	v_cvt_pk_fp8_f32 v101, v127, v131
	s_waitcnt vmcnt(16)
	v_mul_f32_e32 v122, 0x43000000, v186
	v_mul_f32_e32 v123, 0x43000000, v187
	s_waitcnt vmcnt(15)
	v_mul_f32_e32 v126, 0x43000000, v190
	v_mul_f32_e32 v127, 0x43000000, v191
	ds_write2_b32 v84, v93, v97 offset1:32
	ds_write2_b32 v84, v102, v107 offset0:64 offset1:96
	v_cvt_pk_fp8_f32 v110, v100, v104 op_sel:[0,0,1]
	s_waitcnt vmcnt(12)
	v_mul_f32_e32 v100, 0x43000000, v202
	v_mul_f32_e32 v102, 0x43000000, v203
	s_waitcnt vmcnt(11)
	v_mul_f32_e32 v40, 0x43000000, v40
	v_mul_f32_e32 v41, 0x43000000, v41
	s_waitcnt vmcnt(8)
	v_mul_f32_e32 v28, 0x43000000, v28
	v_mul_f32_e32 v29, 0x43000000, v29
	s_waitcnt vmcnt(7)
	v_mul_f32_e32 v24, 0x43000000, v24
	v_mul_f32_e32 v25, 0x43000000, v25
	v_mov_b32_e32 v99, 0
	v_mov_b32_e32 v105, 0
	v_mov_b32_e32 v103, 0
	v_mov_b32_e32 v108, 0
	v_mov_b32_e32 v112, 0
	v_mov_b32_e32 v115, 0
	v_cvt_pk_fp8_f32 v106, v128, v132
	v_mul_f32_e32 v124, 0x43000000, v188
	v_mul_f32_e32 v125, 0x43000000, v189
	v_med3_f32 v122, v122, s10, v81
	v_med3_f32 v123, v123, s10, v81
	v_mul_f32_e32 v128, 0x43000000, v192
	v_mul_f32_e32 v129, 0x43000000, v193
	v_med3_f32 v126, v126, s10, v81
	v_med3_f32 v127, v127, s10, v81
	v_mul_f32_e32 v104, 0x43000000, v204
	v_mul_f32_e32 v107, 0x43000000, v205
	v_med3_f32 v100, v100, s10, v81
	v_med3_f32 v102, v102, s10, v81
	v_mul_f32_e32 v42, 0x43000000, v42
	v_mul_f32_e32 v43, 0x43000000, v43
	v_med3_f32 v40, v40, s10, v81
	v_med3_f32 v41, v41, s10, v81
	v_mul_f32_e32 v30, 0x43000000, v30
	v_mul_f32_e32 v31, 0x43000000, v31
	v_med3_f32 v28, v28, s10, v81
	v_med3_f32 v29, v29, s10, v81
	v_mul_f32_e32 v26, 0x43000000, v26
	v_mul_f32_e32 v27, 0x43000000, v27
	v_med3_f32 v24, v24, s10, v81
	v_med3_f32 v25, v25, s10, v81
	v_mov_b32_e32 v109, 0
	v_mov_b32_e32 v113, 0
	v_mov_b32_e32 v111, 0
	v_mov_b32_e32 v114, 0
	v_mov_b32_e32 v116, 0
	v_mov_b32_e32 v117, 0
	v_mul_f32_e32 v134, 0x43000000, v178
	v_mul_f32_e32 v91, 0x43000000, v182
	v_med3_f32 v124, v124, s10, v81
	v_med3_f32 v125, v125, s10, v81
	v_med3_f32 v128, v128, s10, v81
	v_med3_f32 v129, v129, s10, v81
	v_cvt_pk_fp8_f32 v99, v122, v126
	v_cvt_pk_fp8_f32 v105, v123, v127
	v_med3_f32 v104, v104, s10, v81
	v_med3_f32 v107, v107, s10, v81
	v_med3_f32 v42, v42, s10, v81
	v_med3_f32 v43, v43, s10, v81
	v_cvt_pk_fp8_f32 v103, v100, v40
	v_cvt_pk_fp8_f32 v108, v102, v41
	v_med3_f32 v30, v30, s10, v81
	v_med3_f32 v31, v31, s10, v81
	v_med3_f32 v26, v26, s10, v81
	v_med3_f32 v27, v27, s10, v81
	v_cvt_pk_fp8_f32 v112, v28, v24
	v_cvt_pk_fp8_f32 v115, v29, v25
	s_waitcnt vmcnt(4)
	v_mul_f32_e32 v12, 0x43000000, v12
	v_mul_f32_e32 v13, 0x43000000, v13
	s_waitcnt vmcnt(3)
	v_mul_f32_e32 v8, 0x43000000, v8
	v_mul_f32_e32 v9, 0x43000000, v9
	v_mov_b32_e32 v118, 0
	v_mov_b32_e32 v119, 0
	v_mul_f32_e32 v135, 0x43000000, v179
	v_mul_f32_e32 v136, 0x43000000, v180
	v_med3_f32 v90, v134, s10, v81
	v_mul_f32_e32 v94, 0x43000000, v183
	v_mul_f32_e32 v98, 0x43000000, v184
	v_med3_f32 v91, v91, s10, v81
	v_cvt_pk_fp8_f32 v109, v124, v128
	v_cvt_pk_fp8_f32 v113, v125, v129
	v_cvt_pk_fp8_f32 v111, v104, v42
	v_cvt_pk_fp8_f32 v114, v107, v43
	v_cvt_pk_fp8_f32 v116, v30, v26
	v_cvt_pk_fp8_f32 v117, v31, v27
	v_mul_f32_e32 v14, 0x43000000, v14
	v_mul_f32_e32 v15, 0x43000000, v15
	v_med3_f32 v12, v12, s10, v81
	v_med3_f32 v13, v13, s10, v81
	v_mul_f32_e32 v10, 0x43000000, v10
	v_mul_f32_e32 v11, 0x43000000, v11
	v_med3_f32 v8, v8, s10, v81
	v_med3_f32 v9, v9, s10, v81
	v_mov_b32_e32 v120, 0
	v_mov_b32_e32 v121, 0
	v_med3_f32 v92, v135, s10, v81
	v_med3_f32 v95, v136, s10, v81
	v_med3_f32 v94, v94, s10, v81
	v_med3_f32 v98, v98, s10, v81
	v_mul_f32_e32 v130, 0x43000000, v194
	v_mul_f32_e32 v131, 0x43000000, v195
	v_cvt_pk_fp8_f32 v96, v90, v91 op_sel:[0,0,1]
	v_mul_f32_e32 v91, 0x43000000, v198
	v_mul_f32_e32 v93, 0x43000000, v199
	v_mul_f32_e32 v36, 0x43000000, v36
	v_mul_f32_e32 v37, 0x43000000, v37
	v_mul_f32_e32 v32, 0x43000000, v32
	v_mul_f32_e32 v33, 0x43000000, v33
	v_mul_f32_e32 v20, 0x43000000, v20
	v_mul_f32_e32 v21, 0x43000000, v21
	v_mul_f32_e32 v16, 0x43000000, v16
	v_mul_f32_e32 v17, 0x43000000, v17
	v_med3_f32 v14, v14, s10, v81
	v_med3_f32 v15, v15, s10, v81
	v_med3_f32 v10, v10, s10, v81
	v_med3_f32 v11, v11, s10, v81
	v_cvt_pk_fp8_f32 v118, v12, v8
	v_cvt_pk_fp8_f32 v119, v13, v9
	v_mul_f32_e32 v132, 0x43000000, v196
	v_mul_f32_e32 v133, 0x43000000, v197
	v_cvt_pk_fp8_f32 v101, v92, v94 op_sel:[0,0,1]
	v_cvt_pk_fp8_f32 v106, v95, v98 op_sel:[0,0,1]
	v_med3_f32 v90, v130, s10, v81
	v_med3_f32 v92, v131, s10, v81
	v_mul_f32_e32 v95, 0x43000000, v200
	v_mul_f32_e32 v98, 0x43000000, v201
	v_med3_f32 v91, v91, s10, v81
	v_med3_f32 v93, v93, s10, v81
	v_mul_f32_e32 v38, 0x43000000, v38
	v_mul_f32_e32 v39, 0x43000000, v39
	v_med3_f32 v36, v36, s10, v81
	v_med3_f32 v37, v37, s10, v81
	v_mul_f32_e32 v34, 0x43000000, v34
	v_mul_f32_e32 v35, 0x43000000, v35
	v_med3_f32 v32, v32, s10, v81
	v_med3_f32 v33, v33, s10, v81
	v_mul_f32_e32 v22, 0x43000000, v22
	v_mul_f32_e32 v23, 0x43000000, v23
	v_med3_f32 v20, v20, s10, v81
	v_med3_f32 v21, v21, s10, v81
	v_mul_f32_e32 v18, 0x43000000, v18
	v_mul_f32_e32 v19, 0x43000000, v19
	v_med3_f32 v16, v16, s10, v81
	v_med3_f32 v17, v17, s10, v81
	v_cvt_pk_fp8_f32 v120, v14, v10
	v_cvt_pk_fp8_f32 v121, v15, v11
	v_med3_f32 v94, v132, s10, v81
	v_med3_f32 v97, v133, s10, v81
	v_med3_f32 v95, v95, s10, v81
	v_med3_f32 v98, v98, s10, v81
	v_cvt_pk_fp8_f32 v99, v90, v91 op_sel:[0,0,1]
	v_cvt_pk_fp8_f32 v105, v92, v93 op_sel:[0,0,1]
	v_med3_f32 v38, v38, s10, v81
	v_med3_f32 v39, v39, s10, v81
	v_med3_f32 v34, v34, s10, v81
	v_med3_f32 v35, v35, s10, v81
	v_cvt_pk_fp8_f32 v103, v36, v32 op_sel:[0,0,1]
	v_cvt_pk_fp8_f32 v108, v37, v33 op_sel:[0,0,1]
	v_med3_f32 v22, v22, s10, v81
	v_med3_f32 v23, v23, s10, v81
	v_med3_f32 v18, v18, s10, v81
	v_med3_f32 v19, v19, s10, v81
	s_waitcnt vmcnt(2)
	v_mul_f32_e32 v4, 0x43000000, v4
	v_mul_f32_e32 v5, 0x43000000, v5
	v_cvt_pk_fp8_f32 v112, v20, v16 op_sel:[0,0,1]
	v_cvt_pk_fp8_f32 v115, v21, v17 op_sel:[0,0,1]
	s_waitcnt vmcnt(0)
	v_readfirstlane_b32 s20, v250
	v_mul_f32_e32 v0, 0x43000000, v0
	v_mul_f32_e32 v1, 0x43000000, v1
	v_cvt_pk_fp8_f32 v109, v94, v95 op_sel:[0,0,1]
	v_cvt_pk_fp8_f32 v113, v97, v98 op_sel:[0,0,1]
	v_cvt_pk_fp8_f32 v111, v38, v34 op_sel:[0,0,1]
	v_cvt_pk_fp8_f32 v114, v39, v35 op_sel:[0,0,1]
	v_mul_f32_e32 v6, 0x43000000, v6
	v_mul_f32_e32 v7, 0x43000000, v7
	v_cvt_pk_fp8_f32 v116, v22, v18 op_sel:[0,0,1]
	v_cvt_pk_fp8_f32 v117, v23, v19 op_sel:[0,0,1]
	v_med3_f32 v4, v4, s10, v81
	v_med3_f32 v5, v5, s10, v81
	v_mul_f32_e32 v2, 0x43000000, v2
	v_mul_f32_e32 v3, 0x43000000, v3
	v_med3_f32 v0, v0, s10, v81
	v_med3_f32 v1, v1, s10, v81
	v_med3_f32 v6, v6, s10, v81
	v_med3_f32 v7, v7, s10, v81
	v_med3_f32 v2, v2, s10, v81
	v_med3_f32 v3, v3, s10, v81
	v_cvt_pk_fp8_f32 v118, v4, v0 op_sel:[0,0,1]
	v_cvt_pk_fp8_f32 v119, v5, v1 op_sel:[0,0,1]
	v_cvt_pk_fp8_f32 v120, v6, v2 op_sel:[0,0,1]
	v_cvt_pk_fp8_f32 v121, v7, v3 op_sel:[0,0,1]
	ds_write2_b32 v85, v96, v101 offset1:32
	ds_write2_b32 v85, v106, v110 offset0:64 offset1:96
	ds_write2_b32 v86, v99, v105 offset1:32
	ds_write2_b32 v86, v109, v113 offset0:64 offset1:96
	ds_write2_b32 v87, v103, v108 offset1:32
	ds_write2_b32 v87, v111, v114 offset0:64 offset1:96
	ds_write2_b32 v88, v112, v115 offset1:32
	ds_write2_b32 v88, v116, v117 offset0:64 offset1:96
	ds_write2_b32 v89, v118, v119 offset1:32
	ds_write2_b32 v89, v120, v121 offset0:64 offset1:96
	s_waitcnt lgkmcnt(0)
	ds_read_b128 v[0:3], v66
	ds_read_b128 v[4:7], v68
	ds_read_b128 v[8:11], v70
	ds_read_b128 v[12:15], v72
	ds_read_b128 v[16:19], v74
	ds_read_b128 v[20:23], v76
	ds_read_b128 v[24:27], v78
	ds_read_b128 v[28:31], v80
	s_waitcnt lgkmcnt(7)
	global_store_dwordx4 v[48:49], v[0:3], off
	s_waitcnt lgkmcnt(6)
	global_store_dwordx4 v[50:51], v[4:7], off
	s_waitcnt lgkmcnt(5)
	global_store_dwordx4 v[52:53], v[8:11], off
	s_waitcnt lgkmcnt(4)
	global_store_dwordx4 v[54:55], v[12:15], off
	s_waitcnt lgkmcnt(3)
	global_store_dwordx4 v[56:57], v[16:19], off
	s_waitcnt lgkmcnt(2)
	global_store_dwordx4 v[58:59], v[20:23], off
	s_waitcnt lgkmcnt(1)
	global_store_dwordx4 v[60:61], v[24:27], off
	s_waitcnt lgkmcnt(0)
	global_store_dwordx4 v[62:63], v[28:31], off
	s_waitcnt lgkmcnt(0)
	s_mov_b32 s2, s20
	s_lshl_b32 s6, s2, 1
	s_lshl_b32 s8, s2, 6
	s_sub_u32 s24, s24, 1
	s_cmp_eq_u32 s24, 0
	s_cbranch_scc1 .LBB0_1576
	s_cmpk_lt_i32 s2, 0x1580
	s_cbranch_scc1 .LBB0_1575
